# first grid barrier census: the 16 relaxed counter loads issued back to back, one wait, then summed (was 15 serialised round trips per poll pass)
# baseline (speedup 1.0000x reference)
.LBB0_1000:
	v_readlane_b32 s2, v253, 30
	v_readlane_b32 s3, v253, 31
	v_readlane_b32 s6, v253, 27
	s_waitcnt lgkmcnt(0)
	s_nop 2
	global_load_dword v0, v177, s[2:3] sc1
	v_readlane_b32 s2, v253, 32
	v_readlane_b32 s3, v253, 33
	s_nop 4
	global_load_dword v1, v177, s[2:3] sc1
	v_readlane_b32 s2, v253, 34
	v_readlane_b32 s3, v253, 35
	s_nop 4
	global_load_dword v2, v177, s[2:3] sc1
	v_readlane_b32 s2, v253, 36
	v_readlane_b32 s3, v253, 37
	s_nop 4
	global_load_dword v3, v177, s[2:3] sc1
	v_readlane_b32 s2, v253, 38
	v_readlane_b32 s3, v253, 39
	s_nop 4
	global_load_dword v4, v177, s[2:3] sc1
	v_readlane_b32 s2, v253, 40
	v_readlane_b32 s3, v253, 41
	s_nop 4
	global_load_dword v5, v177, s[2:3] sc1
	v_readlane_b32 s2, v253, 42
	v_readlane_b32 s3, v253, 43
	s_nop 4
	global_load_dword v6, v177, s[2:3] sc1
	v_readlane_b32 s2, v253, 44
	v_readlane_b32 s3, v253, 45
	s_nop 4
	global_load_dword v7, v177, s[2:3] sc1
	v_readlane_b32 s2, v253, 46
	v_readlane_b32 s3, v253, 47
	s_nop 4
	global_load_dword v8, v177, s[2:3] sc1
	v_readlane_b32 s2, v253, 48
	v_readlane_b32 s3, v253, 49
	s_nop 4
	global_load_dword v9, v177, s[2:3] sc1
	v_readlane_b32 s2, v253, 50
	v_readlane_b32 s3, v253, 51
	s_nop 4
	global_load_dword v10, v177, s[2:3] sc1
	v_readlane_b32 s2, v253, 52
	v_readlane_b32 s3, v253, 53
	s_nop 4
	global_load_dword v11, v177, s[2:3] sc1
	v_readlane_b32 s2, v253, 54
	v_readlane_b32 s3, v253, 55
	s_nop 4
	global_load_dword v12, v177, s[2:3] sc1
	v_readlane_b32 s2, v253, 56
	v_readlane_b32 s3, v253, 57
	s_nop 4
	global_load_dword v13, v177, s[2:3] sc1
	v_readlane_b32 s2, v253, 58
	v_readlane_b32 s3, v253, 59
	s_nop 4
	global_load_dword v14, v177, s[2:3] sc1
	v_readlane_b32 s2, v253, 60
	v_readlane_b32 s3, v253, 61
	s_nop 4
	global_load_dword v15, v177, s[2:3] sc1
	s_mov_b64 s[2:3], -1
	s_waitcnt vmcnt(0)
	v_add_u32_e32 v16, v1, v0
	v_add_u32_e32 v16, v16, v2
	v_add_u32_e32 v16, v16, v3
	v_add_u32_e32 v16, v16, v4
	v_add_u32_e32 v16, v16, v5
	v_add_u32_e32 v16, v16, v6
	v_add_u32_e32 v16, v16, v7
	v_add_u32_e32 v16, v16, v8
	v_add_u32_e32 v16, v16, v9
	v_add_u32_e32 v16, v16, v10
	v_add_u32_e32 v16, v16, v11
	v_add_u32_e32 v16, v16, v12
	v_add_u32_e32 v16, v16, v13
	v_add_u32_e32 v16, v16, v14
	v_add_u32_e32 v16, v16, v15
	v_cmp_eq_u32_e32 vcc, s6, v16
	s_mov_b64 s[6:7], -1
	s_cbranch_vccnz .LBB0_999
	s_and_b32 s2, s10, 0xff
	s_cmp_eq_u32 s2, 0
	s_mov_b64 s[2:3], -1
	s_mov_b64 s[8:9], -1
	s_sleep 1
	s_cbranch_scc0 .LBB0_1004
	v_readlane_b32 s2, v253, 28
	v_readlane_b32 s3, v253, 29
	s_nop 4
	global_load_dword v16, v177, s[2:3] sc1
	s_waitcnt vmcnt(0)
	v_cmp_eq_u32_e32 vcc, 0, v16
	s_cbranch_vccnz .LBB0_1006
	s_mov_b64 s[8:9], 0
	s_mov_b64 s[2:3], -1
